# v37 + rs-load hoist in the w_in / xq / KV GEMM epilogue, with s_nop 0 keeping the two wait states between each dwordx4 store and the next VALU write of its data registers
# baseline (speedup 1.0000x reference)
; __device__ __forceinline__ u32x4 pack8(const f32x4 a, const f32x4 b) { u32x4 w; w.x = cvt_pk_bf16(a[0], a[1]); w.y = cvt_pk_bf16(a[2], a[3]); w.z = cvt_pk_bf16(b[0], b[1]); w.w = cvt_pk_bf16(b[2], b[3]); return w; }
;     __device__ __forceinline__ void operator()(const f32x4 (&acc)[2][2][4][2], const Unit& u, int wr, int wc, int fr, int fq) const {
;         const int row0 = u.pm * BM + wr * 64 + fr, col0 = u.pn * BM + wc * 32 + 8 * fq;
; #pragma unroll
;         for (int ai = 0; ai < 2; ++ai)
; #pragma unroll
;             for (int m = 0; m < 4; ++m) { const int row = row0 + ai * HALF + m * 16; bf16_t* rowp = O + (size_t)row * ldc;
;                 float sc = rs[row]; sc = rs_on ? sc : 1.0f;
; #pragma unroll
;                 for (int bj = 0; bj < 2; ++bj) { const int c = col0 + bj * HALF; if (c < ncols) *(u32x4*)(rowp + c) = pack8(acc[ai][bj][m][0] * sc, acc[ai][bj][m][1] * sc); } }
;     }
.LBB0_350:
	v_lshl_add_u32 v142, s98, 8, v150
	v_ashrrev_i32_e32 v143, 31, v142
	v_lshl_add_u64 v[144:145], v[142:143], 2, s[14:15]
	global_load_dword v141, v[144:145], off
	global_load_dword v227, v[144:145], off offset:64
	global_load_dword v246, v[144:145], off offset:128
	global_load_dword v247, v[144:145], off offset:192
	global_load_dword v248, v[144:145], off offset:512
	global_load_dword v249, v[144:145], off offset:576
	global_load_dword v250, v[144:145], off offset:640
	global_load_dword v251, v[144:145], off offset:704
	v_lshl_or_b32 v140, s8, 8, v152
	v_mad_i64_i32 v[146:147], s[8:9], v142, s20, 0
	v_cmp_gt_i32_e32 vcc, s20, v140
	v_lshl_add_u64 v[146:147], v[146:147], 1, s[80:81]
	s_waitcnt vmcnt(0)
	v_cndmask_b32_e64 v148, 1.0, v141, s[82:83]
	v_mov_b32_e32 v149, v148
	v_ashrrev_i32_e32 v141, 31, v140
	s_and_saveexec_b64 s[8:9], vcc
	s_cbranch_execz .LBB0_352
	v_mov_b32_e32 v154, v148
	v_mov_b32_e32 v155, v148
	v_pk_mul_f32 v[126:127], v[126:127], v[148:149]
	v_pk_mul_f32 v[128:129], v[128:129], v[154:155]
	v_pk_mul_f32 v[154:155], v[124:125], v[154:155]
	v_pk_mul_f32 v[124:125], v[122:123], v[148:149]
	v_cvt_pk_bf16_f32 v122, v126, v127
	v_lshl_add_u64 v[126:127], v[140:141], 1, v[146:147]
	v_cvt_pk_bf16_f32 v123, v128, v129
	v_cvt_pk_bf16_f32 v124, v124, v125
	v_cvt_pk_bf16_f32 v125, v154, v155
	global_store_dwordx4 v[126:127], v[122:125], off

; __device__ __forceinline__ u32x4 pack8(const f32x4 a, const f32x4 b) { u32x4 w; w.x = cvt_pk_bf16(a[0], a[1]); w.y = cvt_pk_bf16(a[2], a[3]); w.z = cvt_pk_bf16(b[0], b[1]); w.w = cvt_pk_bf16(b[2], b[3]); return w; }
;     __device__ __forceinline__ void operator()(const f32x4 (&acc)[2][2][4][2], const Unit& u, int wr, int wc, int fr, int fq) const {
;     ...
;             for (int m = 0; m < 4; ++m) { const int row = row0 + ai * HALF + m * 16; bf16_t* rowp = O + (size_t)row * ldc;
;                 float sc = rs[row]; sc = rs_on ? sc : 1.0f;
; #pragma unroll
;                 for (int bj = 0; bj < 2; ++bj) { const int c = col0 + bj * HALF; if (c < ncols) *(u32x4*)(rowp + c) = pack8(acc[ai][bj][m][0] * sc, acc[ai][bj][m][1] * sc); } }
.LBB0_354:
	s_or_b64 exec, exec, s[94:95]
	s_nop 0
	v_or_b32_e32 v114, 16, v142
	v_ashrrev_i32_e32 v115, 31, v114
	v_lshl_add_u64 v[116:117], v[114:115], 2, s[14:15]
	s_nop 0
	v_mad_i64_i32 v[114:115], s[16:17], v114, s20, 0
	v_lshl_add_u64 v[114:115], v[114:115], 1, s[80:81]
	v_mov_b32_e32 v116, v227
	v_cndmask_b32_e64 v116, 1.0, v116, s[82:83]
	v_mov_b32_e32 v117, v116
	s_and_saveexec_b64 s[94:95], vcc
	s_cbranch_execz .LBB0_356
	v_mov_b32_e32 v118, v116
	v_mov_b32_e32 v119, v116
	v_pk_mul_f32 v[110:111], v[110:111], v[116:117]
	v_pk_mul_f32 v[112:113], v[112:113], v[118:119]
	v_pk_mul_f32 v[118:119], v[108:109], v[118:119]
	v_pk_mul_f32 v[108:109], v[106:107], v[116:117]
	v_cvt_pk_bf16_f32 v106, v110, v111
	v_lshl_add_u64 v[110:111], v[140:141], 1, v[114:115]
	v_cvt_pk_bf16_f32 v107, v112, v113
	v_cvt_pk_bf16_f32 v108, v108, v109
	v_cvt_pk_bf16_f32 v109, v118, v119
	global_store_dwordx4 v[110:111], v[106:109], off

; __device__ __forceinline__ u32x4 pack8(const f32x4 a, const f32x4 b) { u32x4 w; w.x = cvt_pk_bf16(a[0], a[1]); w.y = cvt_pk_bf16(a[2], a[3]); w.z = cvt_pk_bf16(b[0], b[1]); w.w = cvt_pk_bf16(b[2], b[3]); return w; }
;     __device__ __forceinline__ void operator()(const f32x4 (&acc)[2][2][4][2], const Unit& u, int wr, int wc, int fr, int fq) const {
;     ...
;             for (int m = 0; m < 4; ++m) { const int row = row0 + ai * HALF + m * 16; bf16_t* rowp = O + (size_t)row * ldc;
;                 float sc = rs[row]; sc = rs_on ? sc : 1.0f;
; #pragma unroll
;                 for (int bj = 0; bj < 2; ++bj) { const int c = col0 + bj * HALF; if (c < ncols) *(u32x4*)(rowp + c) = pack8(acc[ai][bj][m][0] * sc, acc[ai][bj][m][1] * sc); } }
.LBB0_358:
	s_or_b64 exec, exec, s[94:95]
	s_nop 0
	v_or_b32_e32 v98, 32, v142
	v_ashrrev_i32_e32 v99, 31, v98
	v_lshl_add_u64 v[100:101], v[98:99], 2, s[14:15]
	s_nop 0
	v_mad_i64_i32 v[98:99], s[16:17], v98, s20, 0
	v_lshl_add_u64 v[98:99], v[98:99], 1, s[80:81]
	v_mov_b32_e32 v100, v246
	v_cndmask_b32_e64 v100, 1.0, v100, s[82:83]
	v_mov_b32_e32 v101, v100
	s_and_saveexec_b64 s[94:95], vcc
	s_cbranch_execz .LBB0_360
	v_mov_b32_e32 v102, v100
	v_mov_b32_e32 v103, v100
	v_pk_mul_f32 v[94:95], v[94:95], v[100:101]
	v_pk_mul_f32 v[96:97], v[96:97], v[102:103]
	v_pk_mul_f32 v[102:103], v[92:93], v[102:103]
	v_pk_mul_f32 v[92:93], v[90:91], v[100:101]
	v_cvt_pk_bf16_f32 v90, v94, v95
	v_lshl_add_u64 v[94:95], v[140:141], 1, v[98:99]
	v_cvt_pk_bf16_f32 v91, v96, v97
	v_cvt_pk_bf16_f32 v92, v92, v93
	v_cvt_pk_bf16_f32 v93, v102, v103
	global_store_dwordx4 v[94:95], v[90:93], off

; __device__ __forceinline__ u32x4 pack8(const f32x4 a, const f32x4 b) { u32x4 w; w.x = cvt_pk_bf16(a[0], a[1]); w.y = cvt_pk_bf16(a[2], a[3]); w.z = cvt_pk_bf16(b[0], b[1]); w.w = cvt_pk_bf16(b[2], b[3]); return w; }
;     __device__ __forceinline__ void operator()(const f32x4 (&acc)[2][2][4][2], const Unit& u, int wr, int wc, int fr, int fq) const {
;     ...
;             for (int m = 0; m < 4; ++m) { const int row = row0 + ai * HALF + m * 16; bf16_t* rowp = O + (size_t)row * ldc;
;                 float sc = rs[row]; sc = rs_on ? sc : 1.0f;
; #pragma unroll
;                 for (int bj = 0; bj < 2; ++bj) { const int c = col0 + bj * HALF; if (c < ncols) *(u32x4*)(rowp + c) = pack8(acc[ai][bj][m][0] * sc, acc[ai][bj][m][1] * sc); } }
.LBB0_362:
	s_or_b64 exec, exec, s[94:95]
	s_nop 0
	v_or_b32_e32 v82, 48, v142
	v_ashrrev_i32_e32 v83, 31, v82
	v_lshl_add_u64 v[84:85], v[82:83], 2, s[14:15]
	s_nop 0
	v_mad_i64_i32 v[82:83], s[16:17], v82, s20, 0
	v_lshl_add_u64 v[82:83], v[82:83], 1, s[80:81]
	v_mov_b32_e32 v84, v247
	v_cndmask_b32_e64 v84, 1.0, v84, s[82:83]
	v_mov_b32_e32 v85, v84
	s_and_saveexec_b64 s[94:95], vcc
	s_cbranch_execz .LBB0_364
	v_mov_b32_e32 v86, v84
	v_mov_b32_e32 v87, v84
	v_pk_mul_f32 v[78:79], v[78:79], v[84:85]
	v_pk_mul_f32 v[80:81], v[80:81], v[86:87]
	v_pk_mul_f32 v[86:87], v[76:77], v[86:87]
	v_pk_mul_f32 v[76:77], v[74:75], v[84:85]
	v_cvt_pk_bf16_f32 v74, v78, v79
	v_lshl_add_u64 v[78:79], v[140:141], 1, v[82:83]
	v_cvt_pk_bf16_f32 v75, v80, v81
	v_cvt_pk_bf16_f32 v76, v76, v77
	v_cvt_pk_bf16_f32 v77, v86, v87
	global_store_dwordx4 v[78:79], v[74:77], off

; __device__ __forceinline__ u32x4 pack8(const f32x4 a, const f32x4 b) { u32x4 w; w.x = cvt_pk_bf16(a[0], a[1]); w.y = cvt_pk_bf16(a[2], a[3]); w.z = cvt_pk_bf16(b[0], b[1]); w.w = cvt_pk_bf16(b[2], b[3]); return w; }
;     __device__ __forceinline__ void operator()(const f32x4 (&acc)[2][2][4][2], const Unit& u, int wr, int wc, int fr, int fq) const {
;     ...
;             for (int m = 0; m < 4; ++m) { const int row = row0 + ai * HALF + m * 16; bf16_t* rowp = O + (size_t)row * ldc;
;                 float sc = rs[row]; sc = rs_on ? sc : 1.0f;
; #pragma unroll
;                 for (int bj = 0; bj < 2; ++bj) { const int c = col0 + bj * HALF; if (c < ncols) *(u32x4*)(rowp + c) = pack8(acc[ai][bj][m][0] * sc, acc[ai][bj][m][1] * sc); } }
.LBB0_366:
	s_or_b64 exec, exec, s[94:95]
	s_nop 0
	v_add_u32_e32 v66, 0x80, v142
	v_mad_i64_i32 v[66:67], s[16:17], v66, s20, 0
	v_lshl_add_u64 v[66:67], v[66:67], 1, s[80:81]
	v_mov_b32_e32 v68, v248
	v_cndmask_b32_e64 v68, 1.0, v68, s[82:83]
	v_mov_b32_e32 v69, v68
	s_and_saveexec_b64 s[94:95], vcc
	s_cbranch_execz .LBB0_368
	v_mov_b32_e32 v70, v68
	v_mov_b32_e32 v71, v68
	v_pk_mul_f32 v[62:63], v[62:63], v[68:69]
	v_pk_mul_f32 v[64:65], v[64:65], v[70:71]
	v_pk_mul_f32 v[70:71], v[60:61], v[70:71]
	v_pk_mul_f32 v[60:61], v[58:59], v[68:69]
	v_cvt_pk_bf16_f32 v58, v62, v63
	v_lshl_add_u64 v[62:63], v[140:141], 1, v[66:67]
	v_cvt_pk_bf16_f32 v59, v64, v65
	v_cvt_pk_bf16_f32 v60, v60, v61
	v_cvt_pk_bf16_f32 v61, v70, v71
	global_store_dwordx4 v[62:63], v[58:61], off

; __device__ __forceinline__ u32x4 pack8(const f32x4 a, const f32x4 b) { u32x4 w; w.x = cvt_pk_bf16(a[0], a[1]); w.y = cvt_pk_bf16(a[2], a[3]); w.z = cvt_pk_bf16(b[0], b[1]); w.w = cvt_pk_bf16(b[2], b[3]); return w; }
;     __device__ __forceinline__ void operator()(const f32x4 (&acc)[2][2][4][2], const Unit& u, int wr, int wc, int fr, int fq) const {
;     ...
;             for (int m = 0; m < 4; ++m) { const int row = row0 + ai * HALF + m * 16; bf16_t* rowp = O + (size_t)row * ldc;
;                 float sc = rs[row]; sc = rs_on ? sc : 1.0f;
; #pragma unroll
;                 for (int bj = 0; bj < 2; ++bj) { const int c = col0 + bj * HALF; if (c < ncols) *(u32x4*)(rowp + c) = pack8(acc[ai][bj][m][0] * sc, acc[ai][bj][m][1] * sc); } }
.LBB0_370:
	s_or_b64 exec, exec, s[94:95]
	s_nop 0
	v_add_u32_e32 v50, 0x90, v142
	v_mad_i64_i32 v[50:51], s[16:17], v50, s20, 0
	v_lshl_add_u64 v[50:51], v[50:51], 1, s[80:81]
	v_mov_b32_e32 v52, v249
	v_cndmask_b32_e64 v52, 1.0, v52, s[82:83]
	v_mov_b32_e32 v53, v52
	s_and_saveexec_b64 s[94:95], vcc
	s_cbranch_execz .LBB0_372
	v_mov_b32_e32 v54, v52
	v_mov_b32_e32 v55, v52
	v_pk_mul_f32 v[46:47], v[46:47], v[52:53]
	v_pk_mul_f32 v[48:49], v[48:49], v[54:55]
	v_pk_mul_f32 v[54:55], v[44:45], v[54:55]
	v_pk_mul_f32 v[44:45], v[42:43], v[52:53]
	v_cvt_pk_bf16_f32 v42, v46, v47
	v_lshl_add_u64 v[46:47], v[140:141], 1, v[50:51]
	v_cvt_pk_bf16_f32 v43, v48, v49
	v_cvt_pk_bf16_f32 v44, v44, v45
	v_cvt_pk_bf16_f32 v45, v54, v55
	global_store_dwordx4 v[46:47], v[42:45], off

; __device__ __forceinline__ u32x4 pack8(const f32x4 a, const f32x4 b) { u32x4 w; w.x = cvt_pk_bf16(a[0], a[1]); w.y = cvt_pk_bf16(a[2], a[3]); w.z = cvt_pk_bf16(b[0], b[1]); w.w = cvt_pk_bf16(b[2], b[3]); return w; }
;     __device__ __forceinline__ void operator()(const f32x4 (&acc)[2][2][4][2], const Unit& u, int wr, int wc, int fr, int fq) const {
;     ...
;             for (int m = 0; m < 4; ++m) { const int row = row0 + ai * HALF + m * 16; bf16_t* rowp = O + (size_t)row * ldc;
;                 float sc = rs[row]; sc = rs_on ? sc : 1.0f;
; #pragma unroll
;                 for (int bj = 0; bj < 2; ++bj) { const int c = col0 + bj * HALF; if (c < ncols) *(u32x4*)(rowp + c) = pack8(acc[ai][bj][m][0] * sc, acc[ai][bj][m][1] * sc); } }
.LBB0_374:
	s_or_b64 exec, exec, s[94:95]
	s_nop 0
	v_add_u32_e32 v34, 0xa0, v142
	v_mad_i64_i32 v[34:35], s[16:17], v34, s20, 0
	v_lshl_add_u64 v[34:35], v[34:35], 1, s[80:81]
	v_mov_b32_e32 v36, v250
	v_cndmask_b32_e64 v36, 1.0, v36, s[82:83]
	v_mov_b32_e32 v37, v36
	s_and_saveexec_b64 s[94:95], vcc
	s_cbranch_execz .LBB0_376
	v_mov_b32_e32 v38, v36
	v_mov_b32_e32 v39, v36
	v_pk_mul_f32 v[30:31], v[30:31], v[36:37]
	v_pk_mul_f32 v[32:33], v[32:33], v[38:39]
	v_pk_mul_f32 v[38:39], v[28:29], v[38:39]
	v_pk_mul_f32 v[28:29], v[26:27], v[36:37]
	v_cvt_pk_bf16_f32 v26, v30, v31
	v_lshl_add_u64 v[30:31], v[140:141], 1, v[34:35]
	v_cvt_pk_bf16_f32 v27, v32, v33
	v_cvt_pk_bf16_f32 v28, v28, v29
	v_cvt_pk_bf16_f32 v29, v38, v39
	global_store_dwordx4 v[30:31], v[26:29], off

; __device__ __forceinline__ u32x4 pack8(const f32x4 a, const f32x4 b) { u32x4 w; w.x = cvt_pk_bf16(a[0], a[1]); w.y = cvt_pk_bf16(a[2], a[3]); w.z = cvt_pk_bf16(b[0], b[1]); w.w = cvt_pk_bf16(b[2], b[3]); return w; }
;     __device__ __forceinline__ void operator()(const f32x4 (&acc)[2][2][4][2], const Unit& u, int wr, int wc, int fr, int fq) const {
;     ...
;             for (int m = 0; m < 4; ++m) { const int row = row0 + ai * HALF + m * 16; bf16_t* rowp = O + (size_t)row * ldc;
;                 float sc = rs[row]; sc = rs_on ? sc : 1.0f;
; #pragma unroll
;                 for (int bj = 0; bj < 2; ++bj) { const int c = col0 + bj * HALF; if (c < ncols) *(u32x4*)(rowp + c) = pack8(acc[ai][bj][m][0] * sc, acc[ai][bj][m][1] * sc); } }
.LBB0_378:
	s_or_b64 exec, exec, s[94:95]
	s_nop 0
	v_add_u32_e32 v18, 0xb0, v142
	v_mad_i64_i32 v[18:19], s[16:17], v18, s20, 0
	v_lshl_add_u64 v[18:19], v[18:19], 1, s[80:81]
	v_mov_b32_e32 v20, v251
	v_cndmask_b32_e64 v20, 1.0, v20, s[82:83]
	v_mov_b32_e32 v21, v20
	s_and_saveexec_b64 s[94:95], vcc
	s_cbranch_execz .LBB0_381
	v_mov_b32_e32 v22, v20
	v_mov_b32_e32 v23, v20
	v_pk_mul_f32 v[14:15], v[14:15], v[20:21]
	v_pk_mul_f32 v[16:17], v[16:17], v[22:23]
	v_pk_mul_f32 v[22:23], v[12:13], v[22:23]
	v_pk_mul_f32 v[12:13], v[10:11], v[20:21]
	v_cvt_pk_bf16_f32 v10, v14, v15
	v_lshl_add_u64 v[14:15], v[140:141], 1, v[18:19]
	v_cvt_pk_bf16_f32 v11, v16, v17
	v_cvt_pk_bf16_f32 v12, v12, v13
	v_cvt_pk_bf16_f32 v13, v22, v23
	global_store_dwordx4 v[14:15], v[10:13], off
	s_or_b64 exec, exec, s[94:95]
	s_and_saveexec_b64 s[94:95], s[8:9]
	s_cbranch_execnz .LBB0_382
